# v97 + counted vmcnt(4) waits (instead of vmcnt(0)/(1)) in the two register-staged projection loops of the attention items
# speedup vs baseline: 1.0107x; 1.0089x over previous
.LBB0_479:
	s_andn2_b64 vcc, exec, s[0:1]
	s_cbranch_vccnz .LBB0_509
	s_add_i32 s1, s53, 0xffffff80
	s_lshr_b32 s4, s1, 3
	s_mov_b32 s5, s97
	v_readlane_b32 s36, v253, 33
	s_lshl_b64 s[8:9], s[4:5], 20
	v_readlane_b32 s46, v253, 43
	v_readlane_b32 s47, v253, 44
	s_add_u32 s10, s46, s8
	s_addc_u32 s11, s47, s9
	s_lshl_b32 s0, s53, 7
	v_mov_b32_e32 v35, v206
	s_and_b32 s0, s0, 0x380
	s_mov_b32 s5, 0x80000
	v_ashrrev_i32_e32 v34, 3, v35
	v_add_u32_e32 v2, s0, v34
	v_ashrrev_i32_e32 v3, 31, v2
	v_lshlrev_b64 v[2:3], 13, v[2:3]
	v_lshlrev_b32_e32 v0, 4, v35
	v_min_i32_e32 v4, 63, v34
	v_lshl_add_u64 v[66:67], s[82:83], 0, v[2:3]
	v_and_b32_e32 v0, 0x70, v0
	v_ashrrev_i32_e32 v5, 31, v4
	v_lshl_add_u64 v[6:7], v[66:67], 0, v[0:1]
	v_min_i32_e32 v2, 0x7f, v34
	v_lshlrev_b64 v[4:5], 13, v[4:5]
	v_ashrrev_i32_e32 v3, 31, v2
	v_lshl_add_u64 v[4:5], s[10:11], 0, v[4:5]
	s_waitcnt vmcnt(0)
	v_add_co_u32_e32 v22, vcc, s5, v6
	v_lshlrev_b64 v[2:3], 13, v[2:3]
	v_lshl_add_u64 v[4:5], v[4:5], 0, v[0:1]
	s_mov_b64 s[12:13], 0x80000
	v_addc_co_u32_e32 v23, vcc, 0, v7, vcc
	v_lshl_add_u64 v[68:69], s[10:11], 0, v[2:3]
	v_lshl_add_u64 v[8:9], v[4:5], 0, s[12:13]
	v_add_co_u32_e32 v4, vcc, s5, v4
	v_lshl_add_u64 v[2:3], v[68:69], 0, v[0:1]
	s_nop 0
	v_addc_co_u32_e32 v5, vcc, 0, v5, vcc
	global_load_dwordx4 v[26:29], v[4:5], off
	global_load_dwordx4 v[30:33], v[8:9], off offset:128
	global_load_dwordx4 v[10:13], v[2:3], off
	global_load_dwordx4 v[18:21], v[2:3], off offset:128
	global_load_dwordx4 v[14:17], v[22:23], off
	s_nop 0
	global_load_dwordx4 v[22:25], v[22:23], off offset:128
	s_nop 0
	global_load_dwordx4 v[2:5], v[6:7], off
	s_nop 0
	global_load_dwordx4 v[6:9], v[6:7], off offset:128
	v_lshrrev_b32_e32 v0, 4, v35
	v_xor_b32_e32 v36, v0, v35
	v_lshlrev_b32_e32 v36, 4, v36
	v_bfe_u32 v37, v35, 1, 3
	v_and_b32_e32 v36, 0x70, v36
	v_bfe_u32 v78, v35, 6, 2
	v_lshl_or_b32 v80, v34, 7, v36
	v_bitop3_b32 v0, v0, v37, 3 bitop3:0x6c
	v_lshlrev_b32_e32 v36, 5, v35
	v_bfe_u32 v79, v35, 4, 2
	v_lshlrev_b32_e32 v0, 4, v0
	v_and_b32_e32 v81, 0xffffe000, v36
	v_lshlrev_b32_e32 v36, 7, v35
	v_lshlrev_b32_e32 v38, 12, v78
	v_and_b32_e32 v82, 0x780, v36
	v_or_b32_e32 v36, v0, v81
	v_or_b32_e32 v39, v0, v38
	v_bitop3_b32 v0, v79, v37, 4 bitop3:0x36
	v_lshlrev_b32_e32 v0, 4, v0
	v_or_b32_e32 v37, v0, v81
	v_or_b32_e32 v38, v0, v38
	v_and_b32_e32 v0, 7, v35
	v_ashrrev_i32_e32 v35, 31, v34
	v_cmp_gt_i64_e32 vcc, 63, v[34:35]
	v_mov_b32_e32 v42, 0
	s_mov_b32 s5, 0
	v_cndmask_b32_e32 v35, 0, v35, vcc
	v_cndmask_b32_e32 v34, 63, v34, vcc
	v_lshlrev_b64 v[34:35], 13, v[34:35]
	v_lshlrev_b32_e32 v0, 4, v0
	v_lshl_add_u64 v[70:71], s[10:11], 0, v[34:35]
	v_add_u32_e32 v83, v36, v82
	v_add_u32_e32 v84, v39, v82
	v_add_u32_e32 v85, v37, v82
	v_add_u32_e32 v86, v38, v82
	v_mov_b32_e32 v43, v42
	v_mov_b32_e32 v44, v42
	v_mov_b32_e32 v45, v42
	v_mov_b32_e32 v62, v42
	v_mov_b32_e32 v63, v42
	v_mov_b32_e32 v64, v42
	v_mov_b32_e32 v65, v42
	v_mov_b32_e32 v34, v42
	v_mov_b32_e32 v35, v42
	v_mov_b32_e32 v36, v42
	v_mov_b32_e32 v37, v42
	v_mov_b32_e32 v38, v42
	v_mov_b32_e32 v39, v42
	v_mov_b32_e32 v40, v42
	v_mov_b32_e32 v41, v42
	v_mov_b32_e32 v46, v42
	v_mov_b32_e32 v47, v42
	v_mov_b32_e32 v48, v42
	v_mov_b32_e32 v49, v42
	v_mov_b32_e32 v50, v42
	v_mov_b32_e32 v51, v42
	v_mov_b32_e32 v52, v42
	v_mov_b32_e32 v53, v42
	v_mov_b32_e32 v54, v42
	v_mov_b32_e32 v55, v42
	v_mov_b32_e32 v56, v42
	v_mov_b32_e32 v57, v42
	v_mov_b32_e32 v58, v42
	v_mov_b32_e32 v59, v42
	v_mov_b32_e32 v60, v42
	v_mov_b32_e32 v61, v42
	v_readlane_b32 s37, v253, 34
	v_readlane_b32 s38, v253, 35
	v_readlane_b32 s39, v253, 36
	v_readlane_b32 s40, v253, 37
	v_readlane_b32 s41, v253, 38
	v_readlane_b32 s42, v253, 39
	v_readlane_b32 s43, v253, 40
	v_readlane_b32 s44, v253, 41
	v_readlane_b32 s45, v253, 42
	v_readlane_b32 s48, v253, 45
	v_readlane_b32 s49, v253, 46
	v_readlane_b32 s50, v253, 47
	v_readlane_b32 s51, v253, 48
	s_waitcnt vmcnt(0)
	s_branch .LBB0_482

.LBB0_482:
	s_cmp_gt_u32 s5, 29
	s_cselect_b64 s[12:13], -1, 0
	s_and_b64 vcc, exec, s[12:13]
	v_lshl_add_u64 v[76:77], v[66:67], 0, v[0:1]
	v_lshl_add_u64 v[74:75], v[68:69], 0, v[0:1]
	v_lshl_add_u64 v[72:73], v[70:71], 0, v[0:1]
	s_cbranch_vccz .Lrs_t1
	s_waitcnt vmcnt(0)
.Lrs_t1:
	s_waitcnt vmcnt(4)
	ds_write_b128 v80, v[2:5]
	ds_write_b128 v80, v[14:17] offset:8192
	ds_write_b128 v80, v[10:13] offset:32768
	ds_write_b128 v80, v[26:29] offset:40960
	s_waitcnt lgkmcnt(0)
	s_barrier
	s_cbranch_vccnz .LBB0_484
	v_add_co_u32_e32 v10, vcc, 0x80000, v76
	global_load_dwordx4 v[2:5], v[76:77], off offset:256
	s_nop 0
	v_addc_co_u32_e32 v11, vcc, 0, v77, vcc
	v_add_co_u32_e32 v26, vcc, 0x80000, v72
	global_load_dwordx4 v[14:17], v[10:11], off offset:256
	s_nop 0
	global_load_dwordx4 v[10:13], v[74:75], off offset:256
	v_addc_co_u32_e32 v27, vcc, 0, v73, vcc
	global_load_dwordx4 v[26:29], v[26:27], off offset:256
.LBB0_484:
	ds_read_b128 v[88:91], v84 offset:32768
	ds_read_b128 v[92:95], v84 offset:34816
	ds_read_b128 v[96:99], v83
	ds_read_b128 v[100:103], v83 offset:2048
	s_cmp_gt_u32 s5, 28
	s_waitcnt lgkmcnt(1)
	v_mfma_f32_16x16x32_bf16 v[58:61], v[88:91], v[96:99], v[58:61]
	v_mfma_f32_16x16x32_bf16 v[54:57], v[92:95], v[96:99], v[54:57]
	s_waitcnt lgkmcnt(0)
	v_mfma_f32_16x16x32_bf16 v[50:53], v[88:91], v[100:103], v[50:53]
	v_mfma_f32_16x16x32_bf16 v[46:49], v[92:95], v[100:103], v[46:49]
	ds_read_b128 v[96:99], v83 offset:4096
	ds_read_b128 v[100:103], v83 offset:6144
	s_waitcnt lgkmcnt(1)
	v_mfma_f32_16x16x32_bf16 v[104:107], v[88:91], v[96:99], v[38:41]
	s_waitcnt lgkmcnt(0)
	v_mfma_f32_16x16x32_bf16 v[62:65], v[88:91], v[100:103], v[62:65]
	ds_read_b128 v[88:91], v86 offset:32768
	v_mfma_f32_16x16x32_bf16 v[96:99], v[92:95], v[96:99], v[34:37]
	v_mfma_f32_16x16x32_bf16 v[92:95], v[92:95], v[100:103], v[42:45]
	ds_read_b128 v[100:103], v86 offset:34816
	ds_read_b128 v[38:41], v85
	ds_read_b128 v[108:111], v85 offset:2048
	s_waitcnt lgkmcnt(1)
	v_mfma_f32_16x16x32_bf16 v[34:37], v[88:91], v[38:41], v[58:61]
	v_mfma_f32_16x16x32_bf16 v[38:41], v[100:103], v[38:41], v[54:57]
	s_nop 2
	ds_read_b128 v[54:57], v85 offset:4096
	ds_read_b128 v[58:61], v85 offset:6144
	s_cbranch_scc0 .Lrs_m1
	s_waitcnt vmcnt(0)
.Lrs_m1:
	s_waitcnt vmcnt(4)
	ds_write_b128 v80, v[6:9] offset:16384
	ds_write_b128 v80, v[22:25] offset:24576
	ds_write_b128 v80, v[18:21] offset:49152
	ds_write_b128 v80, v[30:33] offset:57344
	s_waitcnt lgkmcnt(6)
	v_mfma_f32_16x16x32_bf16 v[42:45], v[88:91], v[108:111], v[50:53]
	s_waitcnt lgkmcnt(0)
	s_barrier
	v_mfma_f32_16x16x32_bf16 v[46:49], v[100:103], v[108:111], v[46:49]
	v_mfma_f32_16x16x32_bf16 v[50:53], v[88:91], v[54:57], v[104:107]
	v_mfma_f32_16x16x32_bf16 v[54:57], v[100:103], v[54:57], v[96:99]
	v_mfma_f32_16x16x32_bf16 v[62:65], v[88:91], v[58:61], v[62:65]
	v_mfma_f32_16x16x32_bf16 v[58:61], v[100:103], v[58:61], v[92:95]
	s_cbranch_scc1 .LBB0_481
	v_add_co_u32_e32 v18, vcc, 0x80000, v76
	global_load_dwordx4 v[6:9], v[76:77], off offset:384
	s_nop 0
	v_addc_co_u32_e32 v19, vcc, 0, v77, vcc
	v_add_co_u32_e32 v30, vcc, 0x80000, v72
	global_load_dwordx4 v[22:25], v[18:19], off offset:384
	s_nop 0
	global_load_dwordx4 v[18:21], v[74:75], off offset:384
	v_addc_co_u32_e32 v31, vcc, 0, v73, vcc
	global_load_dwordx4 v[30:33], v[30:31], off offset:384
	s_branch .LBB0_481
.LBB0_486:
	v_lshlrev_b32_e32 v0, 2, v82
	s_waitcnt vmcnt(3)
	v_lshlrev_b32_e32 v2, 4, v79
	v_lshl_add_u32 v0, v81, 2, v0
	v_lshl_or_b32 v2, v78, 7, v2
	s_mov_b32 s5, 0x10000
	v_add3_u32 v0, v0, v2, s5
	v_mov_b32_e32 v3, v206
	ds_write_b128 v0, v[58:61]
	ds_write_b128 v0, v[54:57] offset:64
	ds_write_b128 v0, v[50:53] offset:8192
	ds_write_b128 v0, v[46:49] offset:8256
	ds_write_b128 v0, v[38:41] offset:16384
	ds_write_b128 v0, v[34:37] offset:16448
	ds_write_b128 v0, v[62:65] offset:24576
	ds_write_b128 v0, v[42:45] offset:24640
	s_waitcnt lgkmcnt(0)
	s_barrier
	v_readlane_b32 s12, v254, 1
	v_ashrrev_i32_e32 v2, 3, v3
	v_add_u32_e32 v4, s0, v2
	v_ashrrev_i32_e32 v5, 31, v4
	v_lshlrev_b64 v[4:5], 13, v[4:5]
	v_readlane_b32 s13, v254, 2
	v_lshlrev_b32_e32 v0, 4, v3
	s_waitcnt vmcnt(1)
	v_min_i32_e32 v10, 63, v2
	s_add_u32 s10, s10, 0x1000
	v_lshl_add_u64 v[6:7], s[12:13], 0, v[4:5]
	v_and_b32_e32 v0, 0x70, v0
	v_min_i32_e32 v8, 0x7f, v2
	v_ashrrev_i32_e32 v11, 31, v10
	s_addc_u32 s11, s11, 0
	v_lshl_add_u64 v[6:7], v[6:7], 0, v[0:1]
	v_ashrrev_i32_e32 v9, 31, v8
	v_lshlrev_b64 v[10:11], 13, v[10:11]
	s_mov_b32 s5, 0x80000
	v_lshlrev_b64 v[8:9], 13, v[8:9]
	v_lshl_add_u64 v[10:11], s[10:11], 0, v[10:11]
	v_add_co_u32_e32 v16, vcc, s5, v6
	v_lshl_add_u64 v[12:13], s[10:11], 0, v[8:9]
	v_lshl_add_u64 v[10:11], v[10:11], 0, v[0:1]
	s_mov_b64 s[10:11], 0x80000
	v_addc_co_u32_e32 v17, vcc, 0, v7, vcc
	v_lshl_add_u64 v[14:15], v[10:11], 0, s[10:11]
	v_add_co_u32_e32 v10, vcc, s5, v10
	v_lshl_add_u64 v[12:13], v[12:13], 0, v[0:1]
	s_nop 0
	v_addc_co_u32_e32 v11, vcc, 0, v11, vcc
	global_load_dwordx4 v[46:49], v[10:11], off
	global_load_dwordx4 v[50:53], v[14:15], off offset:128
	global_load_dwordx4 v[34:37], v[12:13], off
	global_load_dwordx4 v[38:41], v[12:13], off offset:128
	global_load_dwordx4 v[22:25], v[16:17], off
	global_load_dwordx4 v[30:33], v[16:17], off offset:128
	global_load_dwordx4 v[18:21], v[6:7], off
	global_load_dwordx4 v[26:29], v[6:7], off offset:128
	v_lshrrev_b32_e32 v0, 4, v3
	v_xor_b32_e32 v6, v0, v3
	v_bfe_u32 v7, v3, 1, 3
	v_bfe_u32 v80, v3, 6, 2
	v_ashrrev_i32_e32 v78, 8, v3
	v_lshlrev_b32_e32 v6, 4, v6
	v_bitop3_b32 v0, v0, v7, 3 bitop3:0x6c
	v_bfe_u32 v81, v3, 4, 2
	v_and_b32_e32 v6, 0x70, v6
	v_lshlrev_b32_e32 v0, 4, v0
	v_lshlrev_b32_e32 v82, 13, v78
	v_lshlrev_b32_e32 v10, 12, v80
	v_lshl_or_b32 v84, v2, 7, v6
	v_or_b32_e32 v6, v0, v82
	v_or_b32_e32 v11, v0, v10
	v_bitop3_b32 v0, v81, v7, 4 bitop3:0x36
	v_lshlrev_b32_e32 v0, 4, v0
	v_and_b32_e32 v79, 15, v3
	v_or_b32_e32 v7, v0, v82
	v_or_b32_e32 v10, v0, v10
	v_and_b32_e32 v0, 7, v3
	v_ashrrev_i32_e32 v3, 31, v2
	v_readlane_b32 s36, v253, 33
	v_cmp_gt_i64_e32 vcc, 63, v[2:3]
	v_readlane_b32 s46, v253, 43
	v_readlane_b32 s47, v253, 44
	v_cndmask_b32_e32 v3, 0, v3, vcc
	v_cndmask_b32_e32 v2, 63, v2, vcc
	s_add_u32 s8, s46, s8
	v_lshlrev_b32_e32 v83, 7, v79
	v_lshlrev_b64 v[2:3], 13, v[2:3]
	s_addc_u32 s9, s47, s9
	v_mov_b32_e32 v62, 0
	v_lshlrev_b32_e32 v0, 4, v0
	v_lshl_add_u64 v[66:67], s[8:9], 0, v[2:3]
	v_lshl_add_u64 v[68:69], s[8:9], 0, v[8:9]
	v_lshl_add_u64 v[70:71], s[82:83], 0, v[4:5]
	s_mov_b32 s5, -2
	v_add_u32_e32 v85, v6, v83
	v_add_u32_e32 v86, v11, v83
	v_add_u32_e32 v87, v7, v83
	v_add_u32_e32 v88, v10, v83
	v_mov_b32_e32 v63, v62
	v_mov_b32_e32 v64, v62
	v_mov_b32_e32 v65, v62
	v_mov_b32_e32 v58, v62
	v_mov_b32_e32 v59, v62
	v_mov_b32_e32 v60, v62
	v_mov_b32_e32 v61, v62
	v_mov_b32_e32 v54, v62
	v_mov_b32_e32 v55, v62
	v_mov_b32_e32 v56, v62
	v_mov_b32_e32 v57, v62
	v_mov_b32_e32 v42, v62
	v_mov_b32_e32 v43, v62
	v_mov_b32_e32 v44, v62
	v_mov_b32_e32 v45, v62
	v_mov_b32_e32 v14, v62
	v_mov_b32_e32 v15, v62
	v_mov_b32_e32 v16, v62
	v_mov_b32_e32 v17, v62
	v_mov_b32_e32 v10, v62
	v_mov_b32_e32 v11, v62
	v_mov_b32_e32 v12, v62
	v_mov_b32_e32 v13, v62
	v_mov_b32_e32 v6, v62
	v_mov_b32_e32 v7, v62
	v_mov_b32_e32 v8, v62
	v_mov_b32_e32 v9, v62
	v_mov_b32_e32 v2, v62
	v_mov_b32_e32 v3, v62
	v_mov_b32_e32 v4, v62
	v_mov_b32_e32 v5, v62
	v_readlane_b32 s37, v253, 34
	v_readlane_b32 s38, v253, 35
	v_readlane_b32 s39, v253, 36
	v_readlane_b32 s40, v253, 37
	v_readlane_b32 s41, v253, 38
	v_readlane_b32 s42, v253, 39
	v_readlane_b32 s43, v253, 40
	v_readlane_b32 s44, v253, 41
	v_readlane_b32 s45, v253, 42
	v_readlane_b32 s48, v253, 45
	v_readlane_b32 s49, v253, 46
	v_readlane_b32 s50, v253, 47
	v_readlane_b32 s51, v253, 48
	s_waitcnt vmcnt(1)
	s_branch .LBB0_488

.LBB0_488:
	s_add_i32 s5, s5, 2
	s_cmp_gt_u32 s5, 29
	s_cselect_b64 s[8:9], -1, 0
	s_and_b64 vcc, exec, s[8:9]
	v_lshl_add_u64 v[76:77], v[70:71], 0, v[0:1]
	v_lshl_add_u64 v[74:75], v[68:69], 0, v[0:1]
	v_lshl_add_u64 v[72:73], v[66:67], 0, v[0:1]
	s_cbranch_vccz .Lrs_t2
	s_waitcnt vmcnt(0)
.Lrs_t2:
	s_waitcnt vmcnt(4)
	ds_write_b128 v84, v[18:21]
	ds_write_b128 v84, v[22:25] offset:8192
	ds_write_b128 v84, v[34:37] offset:32768
	ds_write_b128 v84, v[46:49] offset:40960
	s_waitcnt lgkmcnt(0)
	s_barrier
	s_cbranch_vccnz .LBB0_490
	v_add_co_u32_e32 v18, vcc, 0x1000, v76
	s_nop 1
	v_addc_co_u32_e32 v19, vcc, 0, v77, vcc
	v_add_co_u32_e32 v22, vcc, 0x81000, v76
	s_nop 1
	v_addc_co_u32_e32 v23, vcc, 0, v77, vcc
	v_add_co_u32_e32 v34, vcc, 0x1000, v74
	global_load_dwordx4 v[18:21], v[18:19], off offset:256
	s_nop 0
	global_load_dwordx4 v[22:25], v[22:23], off offset:256
	v_addc_co_u32_e32 v35, vcc, 0, v75, vcc
	v_add_co_u32_e32 v46, vcc, 0x81000, v72
	global_load_dwordx4 v[34:37], v[34:35], off offset:256
	s_nop 0
	v_addc_co_u32_e32 v47, vcc, 0, v73, vcc
	global_load_dwordx4 v[46:49], v[46:47], off offset:256
.LBB0_490:
	ds_read_b128 v[90:93], v86 offset:32768
	ds_read_b128 v[94:97], v86 offset:34816
	ds_read_b128 v[98:101], v85
	ds_read_b128 v[102:105], v85 offset:2048
	s_cmp_gt_u32 s5, 28
	s_waitcnt lgkmcnt(1)
	v_mfma_f32_16x16x32_bf16 v[62:65], v[90:93], v[98:101], v[62:65]
	v_mfma_f32_16x16x32_bf16 v[58:61], v[94:97], v[98:101], v[58:61]
	s_waitcnt lgkmcnt(0)
	v_mfma_f32_16x16x32_bf16 v[54:57], v[90:93], v[102:105], v[54:57]
	v_mfma_f32_16x16x32_bf16 v[42:45], v[94:97], v[102:105], v[42:45]
	ds_read_b128 v[98:101], v85 offset:4096
	ds_read_b128 v[102:105], v85 offset:6144
	ds_read_b128 v[106:109], v88 offset:32768
	s_waitcnt lgkmcnt(2)
	v_mfma_f32_16x16x32_bf16 v[14:17], v[90:93], v[98:101], v[14:17]
	v_mfma_f32_16x16x32_bf16 v[98:101], v[94:97], v[98:101], v[10:13]
	s_waitcnt lgkmcnt(1)
	v_mfma_f32_16x16x32_bf16 v[90:93], v[90:93], v[102:105], v[6:9]
	v_mfma_f32_16x16x32_bf16 v[2:5], v[94:97], v[102:105], v[2:5]
	ds_read_b128 v[94:97], v88 offset:34816
	s_nop 0
	ds_read_b128 v[6:9], v87
	ds_read_b128 v[10:13], v87 offset:2048
	s_waitcnt lgkmcnt(1)
	v_mfma_f32_16x16x32_bf16 v[62:65], v[106:109], v[6:9], v[62:65]
	v_mfma_f32_16x16x32_bf16 v[58:61], v[94:97], v[6:9], v[58:61]
	s_waitcnt lgkmcnt(0)
	v_mfma_f32_16x16x32_bf16 v[6:9], v[106:109], v[10:13], v[54:57]
	s_nop 2
	ds_read_b128 v[54:57], v87 offset:4096
	ds_read_b128 v[102:105], v87 offset:6144
	s_cbranch_scc0 .Lrs_m2
	s_waitcnt vmcnt(0)
.Lrs_m2:
	s_waitcnt vmcnt(4)
	ds_write_b128 v84, v[26:29] offset:16384
	ds_write_b128 v84, v[30:33] offset:24576
	ds_write_b128 v84, v[38:41] offset:49152
	ds_write_b128 v84, v[50:53] offset:57344
	v_mfma_f32_16x16x32_bf16 v[10:13], v[94:97], v[10:13], v[42:45]
	s_waitcnt lgkmcnt(0)
	s_barrier
	v_mfma_f32_16x16x32_bf16 v[42:45], v[106:109], v[54:57], v[14:17]
	v_mfma_f32_16x16x32_bf16 v[54:57], v[94:97], v[54:57], v[98:101]
	v_mfma_f32_16x16x32_bf16 v[14:17], v[106:109], v[102:105], v[90:93]
	v_mfma_f32_16x16x32_bf16 v[2:5], v[94:97], v[102:105], v[2:5]
	s_cbranch_scc1 .LBB0_487
	v_add_co_u32_e32 v26, vcc, 0x1000, v76
	s_nop 1
	v_addc_co_u32_e32 v27, vcc, 0, v77, vcc
	v_add_co_u32_e32 v30, vcc, 0x81000, v76
	s_nop 1
	v_addc_co_u32_e32 v31, vcc, 0, v77, vcc
	v_add_co_u32_e32 v38, vcc, 0x1000, v74
	global_load_dwordx4 v[26:29], v[26:27], off offset:384
	s_nop 0
	global_load_dwordx4 v[30:33], v[30:31], off offset:384
	v_addc_co_u32_e32 v39, vcc, 0, v75, vcc
	v_add_co_u32_e32 v50, vcc, 0x81000, v72
	global_load_dwordx4 v[38:41], v[38:39], off offset:384
	s_nop 0
	v_addc_co_u32_e32 v51, vcc, 0, v73, vcc
	global_load_dwordx4 v[50:53], v[50:51], off offset:384
	s_branch .LBB0_487
